# lean attention softmax with packed row-sum adds (scalar subs kept), on v18
# speedup vs baseline: 1.0163x; 1.0061x over previous
; __device__ __forceinline__ void att_qk_sm(const LAS unsigned char* kb, int klane, const bf16x8 (&qf)[12], f32x16 (&o)[4], float& mrun, float& lrun, bf16x8 (&pb)[4]) {
;     ...
;     float ps = 0.f;
; #pragma unroll
;     for (int i = 0; i < 16; ++i) { s0[i] = __builtin_amdgcn_exp2f(s0[i] - mrun); s1[i] = __builtin_amdgcn_exp2f(s1[i] - mrun); ps += s0[i] + s1[i]; }
;     lrun += ps;
;     pb[0] = pack8bf(s0[0], s0[1], s0[2], s0[3], s0[4], s0[5], s0[6], s0[7]);
;     pb[1] = pack8bf(s0[8], s0[9], s0[10], s0[11], s0[12], s0[13], s0[14], s0[15]);
;     pb[2] = pack8bf(s1[0], s1[1], s1[2], s1[3], s1[4], s1[5], s1[6], s1[7]);
;     pb[3] = pack8bf(s1[8], s1[9], s1[10], s1[11], s1[12], s1[13], s1[14], s1[15]);
.LBB0_1021:
	v_mov_b32_e32 v170, v169
	v_sub_f32_e32 v80, v80, v169
	v_sub_f32_e32 v81, v81, v169
	v_sub_f32_e32 v82, v82, v169
	v_sub_f32_e32 v83, v83, v169
	v_sub_f32_e32 v84, v84, v169
	v_sub_f32_e32 v85, v85, v169
	v_sub_f32_e32 v86, v86, v169
	v_sub_f32_e32 v87, v87, v169
	v_sub_f32_e32 v88, v88, v169
	v_sub_f32_e32 v89, v89, v169
	v_sub_f32_e32 v90, v90, v169
	v_sub_f32_e32 v91, v91, v169
	v_sub_f32_e32 v92, v92, v169
	v_sub_f32_e32 v93, v93, v169
	v_sub_f32_e32 v94, v94, v169
	v_sub_f32_e32 v95, v95, v169
	v_sub_f32_e32 v64, v64, v169
	v_sub_f32_e32 v65, v65, v169
	v_sub_f32_e32 v66, v66, v169
	v_sub_f32_e32 v67, v67, v169
	v_sub_f32_e32 v68, v68, v169
	v_sub_f32_e32 v69, v69, v169
	v_sub_f32_e32 v70, v70, v169
	v_sub_f32_e32 v71, v71, v169
	v_sub_f32_e32 v72, v72, v169
	v_sub_f32_e32 v73, v73, v169
	v_sub_f32_e32 v74, v74, v169
	v_sub_f32_e32 v75, v75, v169
	v_sub_f32_e32 v76, v76, v169
	v_sub_f32_e32 v77, v77, v169
	v_sub_f32_e32 v78, v78, v169
	v_sub_f32_e32 v79, v79, v169
	v_exp_f32_e32 v80, v80
	v_exp_f32_e32 v81, v81
	v_exp_f32_e32 v82, v82
	v_exp_f32_e32 v83, v83
	v_exp_f32_e32 v84, v84
	v_exp_f32_e32 v85, v85
	v_exp_f32_e32 v86, v86
	v_exp_f32_e32 v87, v87
	v_exp_f32_e32 v88, v88
	v_exp_f32_e32 v89, v89
	v_exp_f32_e32 v90, v90
	v_exp_f32_e32 v91, v91
	v_exp_f32_e32 v92, v92
	v_exp_f32_e32 v93, v93
	v_exp_f32_e32 v94, v94
	v_exp_f32_e32 v95, v95
	v_exp_f32_e32 v64, v64
	v_exp_f32_e32 v65, v65
	v_exp_f32_e32 v66, v66
	v_exp_f32_e32 v67, v67
	v_exp_f32_e32 v68, v68
	v_exp_f32_e32 v69, v69
	v_exp_f32_e32 v70, v70
	v_exp_f32_e32 v71, v71
	v_exp_f32_e32 v72, v72
	v_exp_f32_e32 v73, v73
	v_exp_f32_e32 v74, v74
	v_exp_f32_e32 v75, v75
	v_exp_f32_e32 v76, v76
	v_exp_f32_e32 v77, v77
	v_exp_f32_e32 v78, v78
	v_exp_f32_e32 v79, v79
	v_pk_add_f32 v[172:173], v[80:81], v[82:83]
	v_pk_add_f32 v[174:175], v[84:85], v[86:87]
	v_pk_add_f32 v[176:177], v[88:89], v[90:91]
	v_pk_add_f32 v[178:179], v[92:93], v[94:95]
	v_pk_add_f32 v[172:173], v[172:173], v[64:65]
	v_pk_add_f32 v[174:175], v[174:175], v[66:67]
	v_pk_add_f32 v[176:177], v[176:177], v[68:69]
	v_pk_add_f32 v[178:179], v[178:179], v[70:71]
	v_pk_add_f32 v[172:173], v[172:173], v[72:73]
	v_pk_add_f32 v[174:175], v[174:175], v[74:75]
	v_pk_add_f32 v[176:177], v[176:177], v[76:77]
	v_pk_add_f32 v[178:179], v[178:179], v[78:79]
	v_pk_add_f32 v[172:173], v[172:173], v[174:175]
	v_pk_add_f32 v[176:177], v[176:177], v[178:179]
	v_cvt_pk_bf16_f32 v71, v70, v71
	v_cvt_pk_bf16_f32 v70, v68, v69
	v_cvt_pk_bf16_f32 v69, v66, v67
	v_cvt_pk_bf16_f32 v68, v64, v65
	v_pk_add_f32 v[172:173], v[172:173], v[176:177]
	v_cvt_pk_bf16_f32 v64, v72, v73
	v_cvt_pk_bf16_f32 v65, v74, v75
	v_cvt_pk_bf16_f32 v66, v76, v77
	v_cvt_pk_bf16_f32 v67, v78, v79
	v_add_f32_e32 v170, v172, v173
	v_cvt_pk_bf16_f32 v72, v88, v89
	v_cvt_pk_bf16_f32 v73, v90, v91
	v_cvt_pk_bf16_f32 v74, v92, v93
	v_cvt_pk_bf16_f32 v75, v94, v95
	v_add_f32_e32 v168, v168, v170
	v_cvt_pk_bf16_f32 v76, v80, v81
	v_cvt_pk_bf16_f32 v77, v82, v83
	v_cvt_pk_bf16_f32 v78, v84, v85
	v_cvt_pk_bf16_f32 v79, v86, v87
